# pooling rewrite, 8 consecutive tokens per wave (row reuse across a wave's iterations), two tokens per iteration
# baseline (speedup 1.0000x reference)
.LBB0_229:
	s_or_b64 exec, exec, s[2:3]
	s_cmp_lg_u32 s26, 3
	s_cselect_b64 s[0:1], -1, 0
	v_writelane_b32 v254, s0, 59
	s_cmp_eq_u32 s26, 3
	s_waitcnt lgkmcnt(0)
	v_writelane_b32 v254, s1, 60
	s_cselect_b64 s[0:1], -1, 0
	v_writelane_b32 v254, s0, 61
	s_barrier
	s_nop 0
	v_writelane_b32 v254, s1, 62
	s_and_b64 s[0:1], s[0:1], exec
	s_cselect_b32 s0, 0, s26
	s_cmp_lg_u32 s0, 0
	s_cselect_b64 s[2:3], -1, 0
	v_writelane_b32 v254, s2, 63
	s_and_b64 vcc, exec, s[2:3]
	s_nop 0
	v_writelane_b32 v255, s3, 0
	v_writelane_b32 v255, s26, 1
	v_writelane_b32 v255, s0, 2
	s_cbranch_vccz .LBB0_245
	s_cmp_lg_u32 s0, 1
	s_mov_b64 s[0:1], -1
	s_cbranch_scc0 .LBB0_288
	s_getreg_b32 s0, hwreg(HW_REG_HW_ID, 0, 6)
	s_and_b32 s0, s0, 63
	s_lshl_b32 s0, s0, 2
	s_add_i32 s0, s0, 0x22ef0
	v_mov_b32_e32 v0, s0
	ds_read_b32 v0, v0
	v_mbcnt_lo_u32_b32 v1, -1, v177
	v_mbcnt_hi_u32_b32 v1, -1, v1
	v_readlane_b32 s30, v254, 31
	v_readlane_b32 s31, v254, 32
	v_readlane_b32 s1, v253, 5
	v_lshlrev_b32_e32 v211, 5, v1
	v_lshrrev_b32_e32 v2, 4, v1
	v_lshlrev_b32_e64 v210, v2, 2
	s_waitcnt lgkmcnt(0)
	v_readfirstlane_b32 s0, v0
	s_nop 0
	s_add_i32 s1, s1, s0
	s_lshl_b32 s5, s1, 3
	s_add_u32 s44, s66, 0x6500000
	s_addc_u32 s45, s67, 0
	s_mov_b32 s1, 0
.Lpool_it:
	s_lshl_b32 s0, s1, 1
	s_add_i32 s0, s0, s5
	s_lshr_b32 s4, s0, 13
	s_mul_i32 s4, s4, 0x2001
	s_add_i32 s4, s4, 1
	s_lshl_b32 s2, s0, 11
	s_add_u32 s2, s2, 0x8800000
	s_add_u32 s50, s66, s2
	s_addc_u32 s51, s67, 0
	s_and_b32 s0, s0, 0x1fff
	s_add_i32 s3, s0, 1
	v_min_u32_e32 v209, s3, v210
	s_add_i32 s2, s3, 1
	v_min_u32_e32 v208, s2, v210
	s_sub_i32 s0, s3, 0
	s_max_i32 s0, s0, 0
	s_add_i32 s0, s0, s4
	s_lshl_b32 s0, s0, 11
	s_add_u32 s12, s44, s0
	s_addc_u32 s13, s45, 0
	global_load_dwordx4 v[0:3], v211, s[12:13]
	global_load_dwordx4 v[4:7], v211, s[12:13] offset:16
	s_sub_i32 s0, s3, 1
	s_max_i32 s0, s0, 0
	s_add_i32 s0, s0, s4
	s_lshl_b32 s0, s0, 11
	s_add_u32 s12, s44, s0
	s_addc_u32 s13, s45, 0
	global_load_dwordx4 v[8:11], v211, s[12:13]
	global_load_dwordx4 v[12:15], v211, s[12:13] offset:16
	s_sub_i32 s0, s3, 2
	s_max_i32 s0, s0, 0
	s_add_i32 s0, s0, s4
	s_lshl_b32 s0, s0, 11
	s_add_u32 s12, s44, s0
	s_addc_u32 s13, s45, 0
	global_load_dwordx4 v[16:19], v211, s[12:13]
	global_load_dwordx4 v[20:23], v211, s[12:13] offset:16
	s_sub_i32 s0, s3, 3
	s_max_i32 s0, s0, 0
	s_add_i32 s0, s0, s4
	s_lshl_b32 s0, s0, 11
	s_add_u32 s12, s44, s0
	s_addc_u32 s13, s45, 0
	global_load_dwordx4 v[24:27], v211, s[12:13]
	global_load_dwordx4 v[28:31], v211, s[12:13] offset:16
	s_sub_i32 s0, s3, 4
	s_max_i32 s0, s0, 0
	s_add_i32 s0, s0, s4
	s_lshl_b32 s0, s0, 11
	s_add_u32 s12, s44, s0
	s_addc_u32 s13, s45, 0
	global_load_dwordx4 v[32:35], v211, s[12:13]
	global_load_dwordx4 v[36:39], v211, s[12:13] offset:16
	s_sub_i32 s0, s3, 5
	s_max_i32 s0, s0, 0
	s_add_i32 s0, s0, s4
	s_lshl_b32 s0, s0, 11
	s_add_u32 s12, s44, s0
	s_addc_u32 s13, s45, 0
	global_load_dwordx4 v[40:43], v211, s[12:13]
	global_load_dwordx4 v[44:47], v211, s[12:13] offset:16
	s_sub_i32 s0, s3, 6
	s_max_i32 s0, s0, 0
	s_add_i32 s0, s0, s4
	s_lshl_b32 s0, s0, 11
	s_add_u32 s12, s44, s0
	s_addc_u32 s13, s45, 0
	global_load_dwordx4 v[48:51], v211, s[12:13]
	global_load_dwordx4 v[52:55], v211, s[12:13] offset:16
	s_sub_i32 s0, s3, 7
	s_max_i32 s0, s0, 0
	s_add_i32 s0, s0, s4
	s_lshl_b32 s0, s0, 11
	s_add_u32 s12, s44, s0
	s_addc_u32 s13, s45, 0
	global_load_dwordx4 v[56:59], v211, s[12:13]
	global_load_dwordx4 v[60:63], v211, s[12:13] offset:16
	s_sub_i32 s0, s3, 8
	s_max_i32 s0, s0, 0
	s_add_i32 s0, s0, s4
	s_lshl_b32 s0, s0, 11
	s_add_u32 s12, s44, s0
	s_addc_u32 s13, s45, 0
	global_load_dwordx4 v[64:67], v211, s[12:13]
	global_load_dwordx4 v[68:71], v211, s[12:13] offset:16
	s_sub_i32 s0, s3, 9
	s_max_i32 s0, s0, 0
	s_add_i32 s0, s0, s4
	s_lshl_b32 s0, s0, 11
	s_add_u32 s12, s44, s0
	s_addc_u32 s13, s45, 0
	global_load_dwordx4 v[72:75], v211, s[12:13]
	global_load_dwordx4 v[76:79], v211, s[12:13] offset:16
	s_sub_i32 s0, s3, 10
	s_max_i32 s0, s0, 0
	s_add_i32 s0, s0, s4
	s_lshl_b32 s0, s0, 11
	s_add_u32 s12, s44, s0
	s_addc_u32 s13, s45, 0
	global_load_dwordx4 v[80:83], v211, s[12:13]
	global_load_dwordx4 v[84:87], v211, s[12:13] offset:16
	s_sub_i32 s0, s3, 11
	s_max_i32 s0, s0, 0
	s_add_i32 s0, s0, s4
	s_lshl_b32 s0, s0, 11
	s_add_u32 s12, s44, s0
	s_addc_u32 s13, s45, 0
	global_load_dwordx4 v[88:91], v211, s[12:13]
	global_load_dwordx4 v[92:95], v211, s[12:13] offset:16
	s_sub_i32 s0, s3, 12
	s_max_i32 s0, s0, 0
	s_add_i32 s0, s0, s4
	s_lshl_b32 s0, s0, 11
	s_add_u32 s12, s44, s0
	s_addc_u32 s13, s45, 0
	global_load_dwordx4 v[96:99], v211, s[12:13]
	global_load_dwordx4 v[100:103], v211, s[12:13] offset:16
	s_sub_i32 s0, s3, 13
	s_max_i32 s0, s0, 0
	s_add_i32 s0, s0, s4
	s_lshl_b32 s0, s0, 11
	s_add_u32 s12, s44, s0
	s_addc_u32 s13, s45, 0
	global_load_dwordx4 v[104:107], v211, s[12:13]
	global_load_dwordx4 v[108:111], v211, s[12:13] offset:16
	s_sub_i32 s0, s3, 14
	s_max_i32 s0, s0, 0
	s_add_i32 s0, s0, s4
	s_lshl_b32 s0, s0, 11
	s_add_u32 s12, s44, s0
	s_addc_u32 s13, s45, 0
	global_load_dwordx4 v[112:115], v211, s[12:13]
	global_load_dwordx4 v[116:119], v211, s[12:13] offset:16
	s_sub_i32 s0, s3, 15
	s_max_i32 s0, s0, 0
	s_add_i32 s0, s0, s4
	s_lshl_b32 s0, s0, 11
	s_add_u32 s12, s44, s0
	s_addc_u32 s13, s45, 0
	global_load_dwordx4 v[120:123], v211, s[12:13]
	global_load_dwordx4 v[124:127], v211, s[12:13] offset:16
	s_sub_i32 s0, s3, 16
	s_max_i32 s0, s0, 0
	s_add_i32 s0, s0, s4
	s_lshl_b32 s0, s0, 11
	s_add_u32 s12, s44, s0
	s_addc_u32 s13, s45, 0
	global_load_dwordx4 v[128:131], v211, s[12:13]
	global_load_dwordx4 v[132:135], v211, s[12:13] offset:16
	s_waitcnt vmcnt(32)
	v_cmp_lt_u32_e32 vcc, 0, v208
	v_lshlrev_b32_e32 v188, 16, v0
	v_and_b32_e32 v189, 0xffff0000, v0
	v_lshlrev_b32_e32 v196, 16, v4
	v_and_b32_e32 v197, 0xffff0000, v4
	v_cndmask_b32_e32 v204, 0, v179, vcc
	v_lshlrev_b32_e32 v190, 16, v1
	v_and_b32_e32 v191, 0xffff0000, v1
	v_lshlrev_b32_e32 v198, 16, v5
	v_and_b32_e32 v199, 0xffff0000, v5
	v_lshlrev_b32_e32 v192, 16, v2
	v_and_b32_e32 v193, 0xffff0000, v2
	v_lshlrev_b32_e32 v200, 16, v6
	v_and_b32_e32 v201, 0xffff0000, v6
	v_lshlrev_b32_e32 v194, 16, v3
	v_and_b32_e32 v195, 0xffff0000, v3
	v_lshlrev_b32_e32 v202, 16, v7
	v_and_b32_e32 v203, 0xffff0000, v7
	v_pk_fma_f32 v[136:137], v[188:189], v[204:205], 0 op_sel_hi:[1,0,0]
	v_pk_fma_f32 v[138:139], v[190:191], v[204:205], 0 op_sel_hi:[1,0,0]
	v_pk_fma_f32 v[140:141], v[192:193], v[204:205], 0 op_sel_hi:[1,0,0]
	v_pk_fma_f32 v[142:143], v[194:195], v[204:205], 0 op_sel_hi:[1,0,0]
	v_pk_fma_f32 v[144:145], v[196:197], v[204:205], 0 op_sel_hi:[1,0,0]
	v_pk_fma_f32 v[146:147], v[198:199], v[204:205], 0 op_sel_hi:[1,0,0]
	v_pk_fma_f32 v[148:149], v[200:201], v[204:205], 0 op_sel_hi:[1,0,0]
	v_pk_fma_f32 v[150:151], v[202:203], v[204:205], 0 op_sel_hi:[1,0,0]
	s_waitcnt vmcnt(30)
	v_cmp_lt_u32_e32 vcc, 1, v208
	v_lshlrev_b32_e32 v188, 16, v8
	v_and_b32_e32 v189, 0xffff0000, v8
	v_lshlrev_b32_e32 v196, 16, v12
	v_and_b32_e32 v197, 0xffff0000, v12
	v_cndmask_b32_e32 v204, 0, v179, vcc
	v_cmp_lt_u32_e32 vcc, 0, v209
	v_lshlrev_b32_e32 v190, 16, v9
	v_and_b32_e32 v191, 0xffff0000, v9
	v_lshlrev_b32_e32 v198, 16, v13
	v_and_b32_e32 v199, 0xffff0000, v13
	v_lshlrev_b32_e32 v192, 16, v10
	v_and_b32_e32 v193, 0xffff0000, v10
	v_lshlrev_b32_e32 v200, 16, v14
	v_and_b32_e32 v201, 0xffff0000, v14
	v_lshlrev_b32_e32 v194, 16, v11
	v_and_b32_e32 v195, 0xffff0000, v11
	v_lshlrev_b32_e32 v202, 16, v15
	v_and_b32_e32 v203, 0xffff0000, v15
	v_cndmask_b32_e32 v206, 0, v179, vcc
	v_pk_fma_f32 v[136:137], v[188:189], v[204:205], v[136:137] op_sel_hi:[1,0,1]
	v_pk_fma_f32 v[138:139], v[190:191], v[204:205], v[138:139] op_sel_hi:[1,0,1]
	v_pk_fma_f32 v[140:141], v[192:193], v[204:205], v[140:141] op_sel_hi:[1,0,1]
	v_pk_fma_f32 v[142:143], v[194:195], v[204:205], v[142:143] op_sel_hi:[1,0,1]
	v_pk_fma_f32 v[144:145], v[196:197], v[204:205], v[144:145] op_sel_hi:[1,0,1]
	v_pk_fma_f32 v[146:147], v[198:199], v[204:205], v[146:147] op_sel_hi:[1,0,1]
	v_pk_fma_f32 v[148:149], v[200:201], v[204:205], v[148:149] op_sel_hi:[1,0,1]
	v_pk_fma_f32 v[150:151], v[202:203], v[204:205], v[150:151] op_sel_hi:[1,0,1]
	v_pk_fma_f32 v[152:153], v[188:189], v[206:207], 0 op_sel_hi:[1,0,0]
	v_pk_fma_f32 v[154:155], v[190:191], v[206:207], 0 op_sel_hi:[1,0,0]
	v_pk_fma_f32 v[156:157], v[192:193], v[206:207], 0 op_sel_hi:[1,0,0]
	v_pk_fma_f32 v[158:159], v[194:195], v[206:207], 0 op_sel_hi:[1,0,0]
	v_pk_fma_f32 v[160:161], v[196:197], v[206:207], 0 op_sel_hi:[1,0,0]
	v_pk_fma_f32 v[162:163], v[198:199], v[206:207], 0 op_sel_hi:[1,0,0]
	v_pk_fma_f32 v[164:165], v[200:201], v[206:207], 0 op_sel_hi:[1,0,0]
	v_pk_fma_f32 v[166:167], v[202:203], v[206:207], 0 op_sel_hi:[1,0,0]
	s_waitcnt vmcnt(28)
	v_cmp_lt_u32_e32 vcc, 2, v208
	v_lshlrev_b32_e32 v188, 16, v16
	v_and_b32_e32 v189, 0xffff0000, v16
	v_lshlrev_b32_e32 v196, 16, v20
	v_and_b32_e32 v197, 0xffff0000, v20
	v_cndmask_b32_e32 v204, 0, v179, vcc
	v_cmp_lt_u32_e32 vcc, 1, v209
	v_lshlrev_b32_e32 v190, 16, v17
	v_and_b32_e32 v191, 0xffff0000, v17
	v_lshlrev_b32_e32 v198, 16, v21
	v_and_b32_e32 v199, 0xffff0000, v21
	v_lshlrev_b32_e32 v192, 16, v18
	v_and_b32_e32 v193, 0xffff0000, v18
	v_lshlrev_b32_e32 v200, 16, v22
	v_and_b32_e32 v201, 0xffff0000, v22
	v_lshlrev_b32_e32 v194, 16, v19
	v_and_b32_e32 v195, 0xffff0000, v19
	v_lshlrev_b32_e32 v202, 16, v23
	v_and_b32_e32 v203, 0xffff0000, v23
	v_cndmask_b32_e32 v206, 0, v179, vcc
	v_pk_fma_f32 v[136:137], v[188:189], v[204:205], v[136:137] op_sel_hi:[1,0,1]
	v_pk_fma_f32 v[138:139], v[190:191], v[204:205], v[138:139] op_sel_hi:[1,0,1]
	v_pk_fma_f32 v[140:141], v[192:193], v[204:205], v[140:141] op_sel_hi:[1,0,1]
	v_pk_fma_f32 v[142:143], v[194:195], v[204:205], v[142:143] op_sel_hi:[1,0,1]
	v_pk_fma_f32 v[144:145], v[196:197], v[204:205], v[144:145] op_sel_hi:[1,0,1]
	v_pk_fma_f32 v[146:147], v[198:199], v[204:205], v[146:147] op_sel_hi:[1,0,1]
	v_pk_fma_f32 v[148:149], v[200:201], v[204:205], v[148:149] op_sel_hi:[1,0,1]
	v_pk_fma_f32 v[150:151], v[202:203], v[204:205], v[150:151] op_sel_hi:[1,0,1]
	v_pk_fma_f32 v[152:153], v[188:189], v[206:207], v[152:153] op_sel_hi:[1,0,1]
	v_pk_fma_f32 v[154:155], v[190:191], v[206:207], v[154:155] op_sel_hi:[1,0,1]
	v_pk_fma_f32 v[156:157], v[192:193], v[206:207], v[156:157] op_sel_hi:[1,0,1]
	v_pk_fma_f32 v[158:159], v[194:195], v[206:207], v[158:159] op_sel_hi:[1,0,1]
	v_pk_fma_f32 v[160:161], v[196:197], v[206:207], v[160:161] op_sel_hi:[1,0,1]
	v_pk_fma_f32 v[162:163], v[198:199], v[206:207], v[162:163] op_sel_hi:[1,0,1]
	v_pk_fma_f32 v[164:165], v[200:201], v[206:207], v[164:165] op_sel_hi:[1,0,1]
	v_pk_fma_f32 v[166:167], v[202:203], v[206:207], v[166:167] op_sel_hi:[1,0,1]
	s_waitcnt vmcnt(26)
	v_cmp_lt_u32_e32 vcc, 3, v208
	v_lshlrev_b32_e32 v188, 16, v24
	v_and_b32_e32 v189, 0xffff0000, v24
	v_lshlrev_b32_e32 v196, 16, v28
	v_and_b32_e32 v197, 0xffff0000, v28
	v_cndmask_b32_e32 v204, 0, v179, vcc
	v_cmp_lt_u32_e32 vcc, 2, v209
	v_lshlrev_b32_e32 v190, 16, v25
	v_and_b32_e32 v191, 0xffff0000, v25
	v_lshlrev_b32_e32 v198, 16, v29
	v_and_b32_e32 v199, 0xffff0000, v29
	v_lshlrev_b32_e32 v192, 16, v26
	v_and_b32_e32 v193, 0xffff0000, v26
	v_lshlrev_b32_e32 v200, 16, v30
	v_and_b32_e32 v201, 0xffff0000, v30
	v_lshlrev_b32_e32 v194, 16, v27
	v_and_b32_e32 v195, 0xffff0000, v27
	v_lshlrev_b32_e32 v202, 16, v31
	v_and_b32_e32 v203, 0xffff0000, v31
	v_cndmask_b32_e32 v206, 0, v179, vcc
	v_pk_fma_f32 v[136:137], v[188:189], v[204:205], v[136:137] op_sel_hi:[1,0,1]
	v_pk_fma_f32 v[138:139], v[190:191], v[204:205], v[138:139] op_sel_hi:[1,0,1]
	v_pk_fma_f32 v[140:141], v[192:193], v[204:205], v[140:141] op_sel_hi:[1,0,1]
	v_pk_fma_f32 v[142:143], v[194:195], v[204:205], v[142:143] op_sel_hi:[1,0,1]
	v_pk_fma_f32 v[144:145], v[196:197], v[204:205], v[144:145] op_sel_hi:[1,0,1]
	v_pk_fma_f32 v[146:147], v[198:199], v[204:205], v[146:147] op_sel_hi:[1,0,1]
	v_pk_fma_f32 v[148:149], v[200:201], v[204:205], v[148:149] op_sel_hi:[1,0,1]
	v_pk_fma_f32 v[150:151], v[202:203], v[204:205], v[150:151] op_sel_hi:[1,0,1]
	v_pk_fma_f32 v[152:153], v[188:189], v[206:207], v[152:153] op_sel_hi:[1,0,1]
	v_pk_fma_f32 v[154:155], v[190:191], v[206:207], v[154:155] op_sel_hi:[1,0,1]
	v_pk_fma_f32 v[156:157], v[192:193], v[206:207], v[156:157] op_sel_hi:[1,0,1]
	v_pk_fma_f32 v[158:159], v[194:195], v[206:207], v[158:159] op_sel_hi:[1,0,1]
	v_pk_fma_f32 v[160:161], v[196:197], v[206:207], v[160:161] op_sel_hi:[1,0,1]
	v_pk_fma_f32 v[162:163], v[198:199], v[206:207], v[162:163] op_sel_hi:[1,0,1]
	v_pk_fma_f32 v[164:165], v[200:201], v[206:207], v[164:165] op_sel_hi:[1,0,1]
	v_pk_fma_f32 v[166:167], v[202:203], v[206:207], v[166:167] op_sel_hi:[1,0,1]
	s_waitcnt vmcnt(24)
	v_cmp_lt_u32_e32 vcc, 4, v208
	v_lshlrev_b32_e32 v188, 16, v32
	v_and_b32_e32 v189, 0xffff0000, v32
	v_lshlrev_b32_e32 v196, 16, v36
	v_and_b32_e32 v197, 0xffff0000, v36
	v_cndmask_b32_e32 v204, 0, v179, vcc
	v_cmp_lt_u32_e32 vcc, 3, v209
	v_lshlrev_b32_e32 v190, 16, v33
	v_and_b32_e32 v191, 0xffff0000, v33
	v_lshlrev_b32_e32 v198, 16, v37
	v_and_b32_e32 v199, 0xffff0000, v37
	v_lshlrev_b32_e32 v192, 16, v34
	v_and_b32_e32 v193, 0xffff0000, v34
	v_lshlrev_b32_e32 v200, 16, v38
	v_and_b32_e32 v201, 0xffff0000, v38
	v_lshlrev_b32_e32 v194, 16, v35
	v_and_b32_e32 v195, 0xffff0000, v35
	v_lshlrev_b32_e32 v202, 16, v39
	v_and_b32_e32 v203, 0xffff0000, v39
	v_cndmask_b32_e32 v206, 0, v179, vcc
	v_pk_fma_f32 v[136:137], v[188:189], v[204:205], v[136:137] op_sel_hi:[1,0,1]
	v_pk_fma_f32 v[138:139], v[190:191], v[204:205], v[138:139] op_sel_hi:[1,0,1]
	v_pk_fma_f32 v[140:141], v[192:193], v[204:205], v[140:141] op_sel_hi:[1,0,1]
	v_pk_fma_f32 v[142:143], v[194:195], v[204:205], v[142:143] op_sel_hi:[1,0,1]
	v_pk_fma_f32 v[144:145], v[196:197], v[204:205], v[144:145] op_sel_hi:[1,0,1]
	v_pk_fma_f32 v[146:147], v[198:199], v[204:205], v[146:147] op_sel_hi:[1,0,1]
	v_pk_fma_f32 v[148:149], v[200:201], v[204:205], v[148:149] op_sel_hi:[1,0,1]
	v_pk_fma_f32 v[150:151], v[202:203], v[204:205], v[150:151] op_sel_hi:[1,0,1]
	v_pk_fma_f32 v[152:153], v[188:189], v[206:207], v[152:153] op_sel_hi:[1,0,1]
	v_pk_fma_f32 v[154:155], v[190:191], v[206:207], v[154:155] op_sel_hi:[1,0,1]
	v_pk_fma_f32 v[156:157], v[192:193], v[206:207], v[156:157] op_sel_hi:[1,0,1]
	v_pk_fma_f32 v[158:159], v[194:195], v[206:207], v[158:159] op_sel_hi:[1,0,1]
	v_pk_fma_f32 v[160:161], v[196:197], v[206:207], v[160:161] op_sel_hi:[1,0,1]
	v_pk_fma_f32 v[162:163], v[198:199], v[206:207], v[162:163] op_sel_hi:[1,0,1]
	v_pk_fma_f32 v[164:165], v[200:201], v[206:207], v[164:165] op_sel_hi:[1,0,1]
	v_pk_fma_f32 v[166:167], v[202:203], v[206:207], v[166:167] op_sel_hi:[1,0,1]
	s_waitcnt vmcnt(22)
	v_cmp_lt_u32_e32 vcc, 5, v208
	v_lshlrev_b32_e32 v188, 16, v40
	v_and_b32_e32 v189, 0xffff0000, v40
	v_lshlrev_b32_e32 v196, 16, v44
	v_and_b32_e32 v197, 0xffff0000, v44
	v_cndmask_b32_e32 v204, 0, v179, vcc
	v_cmp_lt_u32_e32 vcc, 4, v209
	v_lshlrev_b32_e32 v190, 16, v41
	v_and_b32_e32 v191, 0xffff0000, v41
	v_lshlrev_b32_e32 v198, 16, v45
	v_and_b32_e32 v199, 0xffff0000, v45
	v_lshlrev_b32_e32 v192, 16, v42
	v_and_b32_e32 v193, 0xffff0000, v42
	v_lshlrev_b32_e32 v200, 16, v46
	v_and_b32_e32 v201, 0xffff0000, v46
	v_lshlrev_b32_e32 v194, 16, v43
	v_and_b32_e32 v195, 0xffff0000, v43
	v_lshlrev_b32_e32 v202, 16, v47
	v_and_b32_e32 v203, 0xffff0000, v47
	v_cndmask_b32_e32 v206, 0, v179, vcc
	v_pk_fma_f32 v[136:137], v[188:189], v[204:205], v[136:137] op_sel_hi:[1,0,1]
	v_pk_fma_f32 v[138:139], v[190:191], v[204:205], v[138:139] op_sel_hi:[1,0,1]
	v_pk_fma_f32 v[140:141], v[192:193], v[204:205], v[140:141] op_sel_hi:[1,0,1]
	v_pk_fma_f32 v[142:143], v[194:195], v[204:205], v[142:143] op_sel_hi:[1,0,1]
	v_pk_fma_f32 v[144:145], v[196:197], v[204:205], v[144:145] op_sel_hi:[1,0,1]
	v_pk_fma_f32 v[146:147], v[198:199], v[204:205], v[146:147] op_sel_hi:[1,0,1]
	v_pk_fma_f32 v[148:149], v[200:201], v[204:205], v[148:149] op_sel_hi:[1,0,1]
	v_pk_fma_f32 v[150:151], v[202:203], v[204:205], v[150:151] op_sel_hi:[1,0,1]
	v_pk_fma_f32 v[152:153], v[188:189], v[206:207], v[152:153] op_sel_hi:[1,0,1]
	v_pk_fma_f32 v[154:155], v[190:191], v[206:207], v[154:155] op_sel_hi:[1,0,1]
	v_pk_fma_f32 v[156:157], v[192:193], v[206:207], v[156:157] op_sel_hi:[1,0,1]
	v_pk_fma_f32 v[158:159], v[194:195], v[206:207], v[158:159] op_sel_hi:[1,0,1]
	v_pk_fma_f32 v[160:161], v[196:197], v[206:207], v[160:161] op_sel_hi:[1,0,1]
	v_pk_fma_f32 v[162:163], v[198:199], v[206:207], v[162:163] op_sel_hi:[1,0,1]
	v_pk_fma_f32 v[164:165], v[200:201], v[206:207], v[164:165] op_sel_hi:[1,0,1]
	v_pk_fma_f32 v[166:167], v[202:203], v[206:207], v[166:167] op_sel_hi:[1,0,1]
	s_waitcnt vmcnt(20)
	v_cmp_lt_u32_e32 vcc, 6, v208
	v_lshlrev_b32_e32 v188, 16, v48
	v_and_b32_e32 v189, 0xffff0000, v48
	v_lshlrev_b32_e32 v196, 16, v52
	v_and_b32_e32 v197, 0xffff0000, v52
	v_cndmask_b32_e32 v204, 0, v179, vcc
	v_cmp_lt_u32_e32 vcc, 5, v209
	v_lshlrev_b32_e32 v190, 16, v49
	v_and_b32_e32 v191, 0xffff0000, v49
	v_lshlrev_b32_e32 v198, 16, v53
	v_and_b32_e32 v199, 0xffff0000, v53
	v_lshlrev_b32_e32 v192, 16, v50
	v_and_b32_e32 v193, 0xffff0000, v50
	v_lshlrev_b32_e32 v200, 16, v54
	v_and_b32_e32 v201, 0xffff0000, v54
	v_lshlrev_b32_e32 v194, 16, v51
	v_and_b32_e32 v195, 0xffff0000, v51
	v_lshlrev_b32_e32 v202, 16, v55
	v_and_b32_e32 v203, 0xffff0000, v55
	v_cndmask_b32_e32 v206, 0, v179, vcc
	v_pk_fma_f32 v[136:137], v[188:189], v[204:205], v[136:137] op_sel_hi:[1,0,1]
	v_pk_fma_f32 v[138:139], v[190:191], v[204:205], v[138:139] op_sel_hi:[1,0,1]
	v_pk_fma_f32 v[140:141], v[192:193], v[204:205], v[140:141] op_sel_hi:[1,0,1]
	v_pk_fma_f32 v[142:143], v[194:195], v[204:205], v[142:143] op_sel_hi:[1,0,1]
	v_pk_fma_f32 v[144:145], v[196:197], v[204:205], v[144:145] op_sel_hi:[1,0,1]
	v_pk_fma_f32 v[146:147], v[198:199], v[204:205], v[146:147] op_sel_hi:[1,0,1]
	v_pk_fma_f32 v[148:149], v[200:201], v[204:205], v[148:149] op_sel_hi:[1,0,1]
	v_pk_fma_f32 v[150:151], v[202:203], v[204:205], v[150:151] op_sel_hi:[1,0,1]
	v_pk_fma_f32 v[152:153], v[188:189], v[206:207], v[152:153] op_sel_hi:[1,0,1]
	v_pk_fma_f32 v[154:155], v[190:191], v[206:207], v[154:155] op_sel_hi:[1,0,1]
	v_pk_fma_f32 v[156:157], v[192:193], v[206:207], v[156:157] op_sel_hi:[1,0,1]
	v_pk_fma_f32 v[158:159], v[194:195], v[206:207], v[158:159] op_sel_hi:[1,0,1]
	v_pk_fma_f32 v[160:161], v[196:197], v[206:207], v[160:161] op_sel_hi:[1,0,1]
	v_pk_fma_f32 v[162:163], v[198:199], v[206:207], v[162:163] op_sel_hi:[1,0,1]
	v_pk_fma_f32 v[164:165], v[200:201], v[206:207], v[164:165] op_sel_hi:[1,0,1]
	v_pk_fma_f32 v[166:167], v[202:203], v[206:207], v[166:167] op_sel_hi:[1,0,1]
	s_waitcnt vmcnt(18)
	v_cmp_lt_u32_e32 vcc, 7, v208
	v_lshlrev_b32_e32 v188, 16, v56
	v_and_b32_e32 v189, 0xffff0000, v56
	v_lshlrev_b32_e32 v196, 16, v60
	v_and_b32_e32 v197, 0xffff0000, v60
	v_cndmask_b32_e32 v204, 0, v179, vcc
	v_cmp_lt_u32_e32 vcc, 6, v209
	v_lshlrev_b32_e32 v190, 16, v57
	v_and_b32_e32 v191, 0xffff0000, v57
	v_lshlrev_b32_e32 v198, 16, v61
	v_and_b32_e32 v199, 0xffff0000, v61
	v_lshlrev_b32_e32 v192, 16, v58
	v_and_b32_e32 v193, 0xffff0000, v58
	v_lshlrev_b32_e32 v200, 16, v62
	v_and_b32_e32 v201, 0xffff0000, v62
	v_lshlrev_b32_e32 v194, 16, v59
	v_and_b32_e32 v195, 0xffff0000, v59
	v_lshlrev_b32_e32 v202, 16, v63
	v_and_b32_e32 v203, 0xffff0000, v63
	v_cndmask_b32_e32 v206, 0, v179, vcc
	v_pk_fma_f32 v[136:137], v[188:189], v[204:205], v[136:137] op_sel_hi:[1,0,1]
	v_pk_fma_f32 v[138:139], v[190:191], v[204:205], v[138:139] op_sel_hi:[1,0,1]
	v_pk_fma_f32 v[140:141], v[192:193], v[204:205], v[140:141] op_sel_hi:[1,0,1]
	v_pk_fma_f32 v[142:143], v[194:195], v[204:205], v[142:143] op_sel_hi:[1,0,1]
	v_pk_fma_f32 v[144:145], v[196:197], v[204:205], v[144:145] op_sel_hi:[1,0,1]
	v_pk_fma_f32 v[146:147], v[198:199], v[204:205], v[146:147] op_sel_hi:[1,0,1]
	v_pk_fma_f32 v[148:149], v[200:201], v[204:205], v[148:149] op_sel_hi:[1,0,1]
	v_pk_fma_f32 v[150:151], v[202:203], v[204:205], v[150:151] op_sel_hi:[1,0,1]
	v_pk_fma_f32 v[152:153], v[188:189], v[206:207], v[152:153] op_sel_hi:[1,0,1]
	v_pk_fma_f32 v[154:155], v[190:191], v[206:207], v[154:155] op_sel_hi:[1,0,1]
	v_pk_fma_f32 v[156:157], v[192:193], v[206:207], v[156:157] op_sel_hi:[1,0,1]
	v_pk_fma_f32 v[158:159], v[194:195], v[206:207], v[158:159] op_sel_hi:[1,0,1]
	v_pk_fma_f32 v[160:161], v[196:197], v[206:207], v[160:161] op_sel_hi:[1,0,1]
	v_pk_fma_f32 v[162:163], v[198:199], v[206:207], v[162:163] op_sel_hi:[1,0,1]
	v_pk_fma_f32 v[164:165], v[200:201], v[206:207], v[164:165] op_sel_hi:[1,0,1]
	v_pk_fma_f32 v[166:167], v[202:203], v[206:207], v[166:167] op_sel_hi:[1,0,1]
	s_waitcnt vmcnt(16)
	v_cmp_lt_u32_e32 vcc, 8, v208
	v_lshlrev_b32_e32 v188, 16, v64
	v_and_b32_e32 v189, 0xffff0000, v64
	v_lshlrev_b32_e32 v196, 16, v68
	v_and_b32_e32 v197, 0xffff0000, v68
	v_cndmask_b32_e32 v204, 0, v179, vcc
	v_cmp_lt_u32_e32 vcc, 7, v209
	v_lshlrev_b32_e32 v190, 16, v65
	v_and_b32_e32 v191, 0xffff0000, v65
	v_lshlrev_b32_e32 v198, 16, v69
	v_and_b32_e32 v199, 0xffff0000, v69
	v_lshlrev_b32_e32 v192, 16, v66
	v_and_b32_e32 v193, 0xffff0000, v66
	v_lshlrev_b32_e32 v200, 16, v70
	v_and_b32_e32 v201, 0xffff0000, v70
	v_lshlrev_b32_e32 v194, 16, v67
	v_and_b32_e32 v195, 0xffff0000, v67
	v_lshlrev_b32_e32 v202, 16, v71
	v_and_b32_e32 v203, 0xffff0000, v71
	v_cndmask_b32_e32 v206, 0, v179, vcc
	v_pk_fma_f32 v[136:137], v[188:189], v[204:205], v[136:137] op_sel_hi:[1,0,1]
	v_pk_fma_f32 v[138:139], v[190:191], v[204:205], v[138:139] op_sel_hi:[1,0,1]
	v_pk_fma_f32 v[140:141], v[192:193], v[204:205], v[140:141] op_sel_hi:[1,0,1]
	v_pk_fma_f32 v[142:143], v[194:195], v[204:205], v[142:143] op_sel_hi:[1,0,1]
	v_pk_fma_f32 v[144:145], v[196:197], v[204:205], v[144:145] op_sel_hi:[1,0,1]
	v_pk_fma_f32 v[146:147], v[198:199], v[204:205], v[146:147] op_sel_hi:[1,0,1]
	v_pk_fma_f32 v[148:149], v[200:201], v[204:205], v[148:149] op_sel_hi:[1,0,1]
	v_pk_fma_f32 v[150:151], v[202:203], v[204:205], v[150:151] op_sel_hi:[1,0,1]
	v_pk_fma_f32 v[152:153], v[188:189], v[206:207], v[152:153] op_sel_hi:[1,0,1]
	v_pk_fma_f32 v[154:155], v[190:191], v[206:207], v[154:155] op_sel_hi:[1,0,1]
	v_pk_fma_f32 v[156:157], v[192:193], v[206:207], v[156:157] op_sel_hi:[1,0,1]
	v_pk_fma_f32 v[158:159], v[194:195], v[206:207], v[158:159] op_sel_hi:[1,0,1]
	v_pk_fma_f32 v[160:161], v[196:197], v[206:207], v[160:161] op_sel_hi:[1,0,1]
	v_pk_fma_f32 v[162:163], v[198:199], v[206:207], v[162:163] op_sel_hi:[1,0,1]
	v_pk_fma_f32 v[164:165], v[200:201], v[206:207], v[164:165] op_sel_hi:[1,0,1]
	v_pk_fma_f32 v[166:167], v[202:203], v[206:207], v[166:167] op_sel_hi:[1,0,1]
	s_waitcnt vmcnt(14)
	v_cmp_lt_u32_e32 vcc, 9, v208
	v_lshlrev_b32_e32 v188, 16, v72
	v_and_b32_e32 v189, 0xffff0000, v72
	v_lshlrev_b32_e32 v196, 16, v76
	v_and_b32_e32 v197, 0xffff0000, v76
	v_cndmask_b32_e32 v204, 0, v179, vcc
	v_cmp_lt_u32_e32 vcc, 8, v209
	v_lshlrev_b32_e32 v190, 16, v73
	v_and_b32_e32 v191, 0xffff0000, v73
	v_lshlrev_b32_e32 v198, 16, v77
	v_and_b32_e32 v199, 0xffff0000, v77
	v_lshlrev_b32_e32 v192, 16, v74
	v_and_b32_e32 v193, 0xffff0000, v74
	v_lshlrev_b32_e32 v200, 16, v78
	v_and_b32_e32 v201, 0xffff0000, v78
	v_lshlrev_b32_e32 v194, 16, v75
	v_and_b32_e32 v195, 0xffff0000, v75
	v_lshlrev_b32_e32 v202, 16, v79
	v_and_b32_e32 v203, 0xffff0000, v79
	v_cndmask_b32_e32 v206, 0, v179, vcc
	v_pk_fma_f32 v[136:137], v[188:189], v[204:205], v[136:137] op_sel_hi:[1,0,1]
	v_pk_fma_f32 v[138:139], v[190:191], v[204:205], v[138:139] op_sel_hi:[1,0,1]
	v_pk_fma_f32 v[140:141], v[192:193], v[204:205], v[140:141] op_sel_hi:[1,0,1]
	v_pk_fma_f32 v[142:143], v[194:195], v[204:205], v[142:143] op_sel_hi:[1,0,1]
	v_pk_fma_f32 v[144:145], v[196:197], v[204:205], v[144:145] op_sel_hi:[1,0,1]
	v_pk_fma_f32 v[146:147], v[198:199], v[204:205], v[146:147] op_sel_hi:[1,0,1]
	v_pk_fma_f32 v[148:149], v[200:201], v[204:205], v[148:149] op_sel_hi:[1,0,1]
	v_pk_fma_f32 v[150:151], v[202:203], v[204:205], v[150:151] op_sel_hi:[1,0,1]
	v_pk_fma_f32 v[152:153], v[188:189], v[206:207], v[152:153] op_sel_hi:[1,0,1]
	v_pk_fma_f32 v[154:155], v[190:191], v[206:207], v[154:155] op_sel_hi:[1,0,1]
	v_pk_fma_f32 v[156:157], v[192:193], v[206:207], v[156:157] op_sel_hi:[1,0,1]
	v_pk_fma_f32 v[158:159], v[194:195], v[206:207], v[158:159] op_sel_hi:[1,0,1]
	v_pk_fma_f32 v[160:161], v[196:197], v[206:207], v[160:161] op_sel_hi:[1,0,1]
	v_pk_fma_f32 v[162:163], v[198:199], v[206:207], v[162:163] op_sel_hi:[1,0,1]
	v_pk_fma_f32 v[164:165], v[200:201], v[206:207], v[164:165] op_sel_hi:[1,0,1]
	v_pk_fma_f32 v[166:167], v[202:203], v[206:207], v[166:167] op_sel_hi:[1,0,1]
	s_waitcnt vmcnt(12)
	v_cmp_lt_u32_e32 vcc, 10, v208
	v_lshlrev_b32_e32 v188, 16, v80
	v_and_b32_e32 v189, 0xffff0000, v80
	v_lshlrev_b32_e32 v196, 16, v84
	v_and_b32_e32 v197, 0xffff0000, v84
	v_cndmask_b32_e32 v204, 0, v179, vcc
	v_cmp_lt_u32_e32 vcc, 9, v209
	v_lshlrev_b32_e32 v190, 16, v81
	v_and_b32_e32 v191, 0xffff0000, v81
	v_lshlrev_b32_e32 v198, 16, v85
	v_and_b32_e32 v199, 0xffff0000, v85
	v_lshlrev_b32_e32 v192, 16, v82
	v_and_b32_e32 v193, 0xffff0000, v82
	v_lshlrev_b32_e32 v200, 16, v86
	v_and_b32_e32 v201, 0xffff0000, v86
	v_lshlrev_b32_e32 v194, 16, v83
	v_and_b32_e32 v195, 0xffff0000, v83
	v_lshlrev_b32_e32 v202, 16, v87
	v_and_b32_e32 v203, 0xffff0000, v87
	v_cndmask_b32_e32 v206, 0, v179, vcc
	v_pk_fma_f32 v[136:137], v[188:189], v[204:205], v[136:137] op_sel_hi:[1,0,1]
	v_pk_fma_f32 v[138:139], v[190:191], v[204:205], v[138:139] op_sel_hi:[1,0,1]
	v_pk_fma_f32 v[140:141], v[192:193], v[204:205], v[140:141] op_sel_hi:[1,0,1]
	v_pk_fma_f32 v[142:143], v[194:195], v[204:205], v[142:143] op_sel_hi:[1,0,1]
	v_pk_fma_f32 v[144:145], v[196:197], v[204:205], v[144:145] op_sel_hi:[1,0,1]
	v_pk_fma_f32 v[146:147], v[198:199], v[204:205], v[146:147] op_sel_hi:[1,0,1]
	v_pk_fma_f32 v[148:149], v[200:201], v[204:205], v[148:149] op_sel_hi:[1,0,1]
	v_pk_fma_f32 v[150:151], v[202:203], v[204:205], v[150:151] op_sel_hi:[1,0,1]
	v_pk_fma_f32 v[152:153], v[188:189], v[206:207], v[152:153] op_sel_hi:[1,0,1]
	v_pk_fma_f32 v[154:155], v[190:191], v[206:207], v[154:155] op_sel_hi:[1,0,1]
	v_pk_fma_f32 v[156:157], v[192:193], v[206:207], v[156:157] op_sel_hi:[1,0,1]
	v_pk_fma_f32 v[158:159], v[194:195], v[206:207], v[158:159] op_sel_hi:[1,0,1]
	v_pk_fma_f32 v[160:161], v[196:197], v[206:207], v[160:161] op_sel_hi:[1,0,1]
	v_pk_fma_f32 v[162:163], v[198:199], v[206:207], v[162:163] op_sel_hi:[1,0,1]
	v_pk_fma_f32 v[164:165], v[200:201], v[206:207], v[164:165] op_sel_hi:[1,0,1]
	v_pk_fma_f32 v[166:167], v[202:203], v[206:207], v[166:167] op_sel_hi:[1,0,1]
	s_waitcnt vmcnt(10)
	v_cmp_lt_u32_e32 vcc, 11, v208
	v_lshlrev_b32_e32 v188, 16, v88
	v_and_b32_e32 v189, 0xffff0000, v88
	v_lshlrev_b32_e32 v196, 16, v92
	v_and_b32_e32 v197, 0xffff0000, v92
	v_cndmask_b32_e32 v204, 0, v179, vcc
	v_cmp_lt_u32_e32 vcc, 10, v209
	v_lshlrev_b32_e32 v190, 16, v89
	v_and_b32_e32 v191, 0xffff0000, v89
	v_lshlrev_b32_e32 v198, 16, v93
	v_and_b32_e32 v199, 0xffff0000, v93
	v_lshlrev_b32_e32 v192, 16, v90
	v_and_b32_e32 v193, 0xffff0000, v90
	v_lshlrev_b32_e32 v200, 16, v94
	v_and_b32_e32 v201, 0xffff0000, v94
	v_lshlrev_b32_e32 v194, 16, v91
	v_and_b32_e32 v195, 0xffff0000, v91
	v_lshlrev_b32_e32 v202, 16, v95
	v_and_b32_e32 v203, 0xffff0000, v95
	v_cndmask_b32_e32 v206, 0, v179, vcc
	v_pk_fma_f32 v[136:137], v[188:189], v[204:205], v[136:137] op_sel_hi:[1,0,1]
	v_pk_fma_f32 v[138:139], v[190:191], v[204:205], v[138:139] op_sel_hi:[1,0,1]
	v_pk_fma_f32 v[140:141], v[192:193], v[204:205], v[140:141] op_sel_hi:[1,0,1]
	v_pk_fma_f32 v[142:143], v[194:195], v[204:205], v[142:143] op_sel_hi:[1,0,1]
	v_pk_fma_f32 v[144:145], v[196:197], v[204:205], v[144:145] op_sel_hi:[1,0,1]
	v_pk_fma_f32 v[146:147], v[198:199], v[204:205], v[146:147] op_sel_hi:[1,0,1]
	v_pk_fma_f32 v[148:149], v[200:201], v[204:205], v[148:149] op_sel_hi:[1,0,1]
	v_pk_fma_f32 v[150:151], v[202:203], v[204:205], v[150:151] op_sel_hi:[1,0,1]
	v_pk_fma_f32 v[152:153], v[188:189], v[206:207], v[152:153] op_sel_hi:[1,0,1]
	v_pk_fma_f32 v[154:155], v[190:191], v[206:207], v[154:155] op_sel_hi:[1,0,1]
	v_pk_fma_f32 v[156:157], v[192:193], v[206:207], v[156:157] op_sel_hi:[1,0,1]
	v_pk_fma_f32 v[158:159], v[194:195], v[206:207], v[158:159] op_sel_hi:[1,0,1]
	v_pk_fma_f32 v[160:161], v[196:197], v[206:207], v[160:161] op_sel_hi:[1,0,1]
	v_pk_fma_f32 v[162:163], v[198:199], v[206:207], v[162:163] op_sel_hi:[1,0,1]
	v_pk_fma_f32 v[164:165], v[200:201], v[206:207], v[164:165] op_sel_hi:[1,0,1]
	v_pk_fma_f32 v[166:167], v[202:203], v[206:207], v[166:167] op_sel_hi:[1,0,1]
	s_waitcnt vmcnt(8)
	v_cmp_lt_u32_e32 vcc, 12, v208
	v_lshlrev_b32_e32 v188, 16, v96
	v_and_b32_e32 v189, 0xffff0000, v96
	v_lshlrev_b32_e32 v196, 16, v100
	v_and_b32_e32 v197, 0xffff0000, v100
	v_cndmask_b32_e32 v204, 0, v179, vcc
	v_cmp_lt_u32_e32 vcc, 11, v209
	v_lshlrev_b32_e32 v190, 16, v97
	v_and_b32_e32 v191, 0xffff0000, v97
	v_lshlrev_b32_e32 v198, 16, v101
	v_and_b32_e32 v199, 0xffff0000, v101
	v_lshlrev_b32_e32 v192, 16, v98
	v_and_b32_e32 v193, 0xffff0000, v98
	v_lshlrev_b32_e32 v200, 16, v102
	v_and_b32_e32 v201, 0xffff0000, v102
	v_lshlrev_b32_e32 v194, 16, v99
	v_and_b32_e32 v195, 0xffff0000, v99
	v_lshlrev_b32_e32 v202, 16, v103
	v_and_b32_e32 v203, 0xffff0000, v103
	v_cndmask_b32_e32 v206, 0, v179, vcc
	v_pk_fma_f32 v[136:137], v[188:189], v[204:205], v[136:137] op_sel_hi:[1,0,1]
	v_pk_fma_f32 v[138:139], v[190:191], v[204:205], v[138:139] op_sel_hi:[1,0,1]
	v_pk_fma_f32 v[140:141], v[192:193], v[204:205], v[140:141] op_sel_hi:[1,0,1]
	v_pk_fma_f32 v[142:143], v[194:195], v[204:205], v[142:143] op_sel_hi:[1,0,1]
	v_pk_fma_f32 v[144:145], v[196:197], v[204:205], v[144:145] op_sel_hi:[1,0,1]
	v_pk_fma_f32 v[146:147], v[198:199], v[204:205], v[146:147] op_sel_hi:[1,0,1]
	v_pk_fma_f32 v[148:149], v[200:201], v[204:205], v[148:149] op_sel_hi:[1,0,1]
	v_pk_fma_f32 v[150:151], v[202:203], v[204:205], v[150:151] op_sel_hi:[1,0,1]
	v_pk_fma_f32 v[152:153], v[188:189], v[206:207], v[152:153] op_sel_hi:[1,0,1]
	v_pk_fma_f32 v[154:155], v[190:191], v[206:207], v[154:155] op_sel_hi:[1,0,1]
	v_pk_fma_f32 v[156:157], v[192:193], v[206:207], v[156:157] op_sel_hi:[1,0,1]
	v_pk_fma_f32 v[158:159], v[194:195], v[206:207], v[158:159] op_sel_hi:[1,0,1]
	v_pk_fma_f32 v[160:161], v[196:197], v[206:207], v[160:161] op_sel_hi:[1,0,1]
	v_pk_fma_f32 v[162:163], v[198:199], v[206:207], v[162:163] op_sel_hi:[1,0,1]
	v_pk_fma_f32 v[164:165], v[200:201], v[206:207], v[164:165] op_sel_hi:[1,0,1]
	v_pk_fma_f32 v[166:167], v[202:203], v[206:207], v[166:167] op_sel_hi:[1,0,1]
	s_waitcnt vmcnt(6)
	v_cmp_lt_u32_e32 vcc, 13, v208
	v_lshlrev_b32_e32 v188, 16, v104
	v_and_b32_e32 v189, 0xffff0000, v104
	v_lshlrev_b32_e32 v196, 16, v108
	v_and_b32_e32 v197, 0xffff0000, v108
	v_cndmask_b32_e32 v204, 0, v179, vcc
	v_cmp_lt_u32_e32 vcc, 12, v209
	v_lshlrev_b32_e32 v190, 16, v105
	v_and_b32_e32 v191, 0xffff0000, v105
	v_lshlrev_b32_e32 v198, 16, v109
	v_and_b32_e32 v199, 0xffff0000, v109
	v_lshlrev_b32_e32 v192, 16, v106
	v_and_b32_e32 v193, 0xffff0000, v106
	v_lshlrev_b32_e32 v200, 16, v110
	v_and_b32_e32 v201, 0xffff0000, v110
	v_lshlrev_b32_e32 v194, 16, v107
	v_and_b32_e32 v195, 0xffff0000, v107
	v_lshlrev_b32_e32 v202, 16, v111
	v_and_b32_e32 v203, 0xffff0000, v111
	v_cndmask_b32_e32 v206, 0, v179, vcc
	v_pk_fma_f32 v[136:137], v[188:189], v[204:205], v[136:137] op_sel_hi:[1,0,1]
	v_pk_fma_f32 v[138:139], v[190:191], v[204:205], v[138:139] op_sel_hi:[1,0,1]
	v_pk_fma_f32 v[140:141], v[192:193], v[204:205], v[140:141] op_sel_hi:[1,0,1]
	v_pk_fma_f32 v[142:143], v[194:195], v[204:205], v[142:143] op_sel_hi:[1,0,1]
	v_pk_fma_f32 v[144:145], v[196:197], v[204:205], v[144:145] op_sel_hi:[1,0,1]
	v_pk_fma_f32 v[146:147], v[198:199], v[204:205], v[146:147] op_sel_hi:[1,0,1]
	v_pk_fma_f32 v[148:149], v[200:201], v[204:205], v[148:149] op_sel_hi:[1,0,1]
	v_pk_fma_f32 v[150:151], v[202:203], v[204:205], v[150:151] op_sel_hi:[1,0,1]
	v_pk_fma_f32 v[152:153], v[188:189], v[206:207], v[152:153] op_sel_hi:[1,0,1]
	v_pk_fma_f32 v[154:155], v[190:191], v[206:207], v[154:155] op_sel_hi:[1,0,1]
	v_pk_fma_f32 v[156:157], v[192:193], v[206:207], v[156:157] op_sel_hi:[1,0,1]
	v_pk_fma_f32 v[158:159], v[194:195], v[206:207], v[158:159] op_sel_hi:[1,0,1]
	v_pk_fma_f32 v[160:161], v[196:197], v[206:207], v[160:161] op_sel_hi:[1,0,1]
	v_pk_fma_f32 v[162:163], v[198:199], v[206:207], v[162:163] op_sel_hi:[1,0,1]
	v_pk_fma_f32 v[164:165], v[200:201], v[206:207], v[164:165] op_sel_hi:[1,0,1]
	v_pk_fma_f32 v[166:167], v[202:203], v[206:207], v[166:167] op_sel_hi:[1,0,1]
	s_waitcnt vmcnt(4)
	v_cmp_lt_u32_e32 vcc, 14, v208
	v_lshlrev_b32_e32 v188, 16, v112
	v_and_b32_e32 v189, 0xffff0000, v112
	v_lshlrev_b32_e32 v196, 16, v116
	v_and_b32_e32 v197, 0xffff0000, v116
	v_cndmask_b32_e32 v204, 0, v179, vcc
	v_cmp_lt_u32_e32 vcc, 13, v209
	v_lshlrev_b32_e32 v190, 16, v113
	v_and_b32_e32 v191, 0xffff0000, v113
	v_lshlrev_b32_e32 v198, 16, v117
	v_and_b32_e32 v199, 0xffff0000, v117
	v_lshlrev_b32_e32 v192, 16, v114
	v_and_b32_e32 v193, 0xffff0000, v114
	v_lshlrev_b32_e32 v200, 16, v118
	v_and_b32_e32 v201, 0xffff0000, v118
	v_lshlrev_b32_e32 v194, 16, v115
	v_and_b32_e32 v195, 0xffff0000, v115
	v_lshlrev_b32_e32 v202, 16, v119
	v_and_b32_e32 v203, 0xffff0000, v119
	v_cndmask_b32_e32 v206, 0, v179, vcc
	v_pk_fma_f32 v[136:137], v[188:189], v[204:205], v[136:137] op_sel_hi:[1,0,1]
	v_pk_fma_f32 v[138:139], v[190:191], v[204:205], v[138:139] op_sel_hi:[1,0,1]
	v_pk_fma_f32 v[140:141], v[192:193], v[204:205], v[140:141] op_sel_hi:[1,0,1]
	v_pk_fma_f32 v[142:143], v[194:195], v[204:205], v[142:143] op_sel_hi:[1,0,1]
	v_pk_fma_f32 v[144:145], v[196:197], v[204:205], v[144:145] op_sel_hi:[1,0,1]
	v_pk_fma_f32 v[146:147], v[198:199], v[204:205], v[146:147] op_sel_hi:[1,0,1]
	v_pk_fma_f32 v[148:149], v[200:201], v[204:205], v[148:149] op_sel_hi:[1,0,1]
	v_pk_fma_f32 v[150:151], v[202:203], v[204:205], v[150:151] op_sel_hi:[1,0,1]
	v_pk_fma_f32 v[152:153], v[188:189], v[206:207], v[152:153] op_sel_hi:[1,0,1]
	v_pk_fma_f32 v[154:155], v[190:191], v[206:207], v[154:155] op_sel_hi:[1,0,1]
	v_pk_fma_f32 v[156:157], v[192:193], v[206:207], v[156:157] op_sel_hi:[1,0,1]
	v_pk_fma_f32 v[158:159], v[194:195], v[206:207], v[158:159] op_sel_hi:[1,0,1]
	v_pk_fma_f32 v[160:161], v[196:197], v[206:207], v[160:161] op_sel_hi:[1,0,1]
	v_pk_fma_f32 v[162:163], v[198:199], v[206:207], v[162:163] op_sel_hi:[1,0,1]
	v_pk_fma_f32 v[164:165], v[200:201], v[206:207], v[164:165] op_sel_hi:[1,0,1]
	v_pk_fma_f32 v[166:167], v[202:203], v[206:207], v[166:167] op_sel_hi:[1,0,1]
	s_waitcnt vmcnt(2)
	v_cmp_lt_u32_e32 vcc, 15, v208
	v_lshlrev_b32_e32 v188, 16, v120
	v_and_b32_e32 v189, 0xffff0000, v120
	v_lshlrev_b32_e32 v196, 16, v124
	v_and_b32_e32 v197, 0xffff0000, v124
	v_cndmask_b32_e32 v204, 0, v179, vcc
	v_cmp_lt_u32_e32 vcc, 14, v209
	v_lshlrev_b32_e32 v190, 16, v121
	v_and_b32_e32 v191, 0xffff0000, v121
	v_lshlrev_b32_e32 v198, 16, v125
	v_and_b32_e32 v199, 0xffff0000, v125
	v_lshlrev_b32_e32 v192, 16, v122
	v_and_b32_e32 v193, 0xffff0000, v122
	v_lshlrev_b32_e32 v200, 16, v126
	v_and_b32_e32 v201, 0xffff0000, v126
	v_lshlrev_b32_e32 v194, 16, v123
	v_and_b32_e32 v195, 0xffff0000, v123
	v_lshlrev_b32_e32 v202, 16, v127
	v_and_b32_e32 v203, 0xffff0000, v127
	v_cndmask_b32_e32 v206, 0, v179, vcc
	v_pk_fma_f32 v[136:137], v[188:189], v[204:205], v[136:137] op_sel_hi:[1,0,1]
	v_pk_fma_f32 v[138:139], v[190:191], v[204:205], v[138:139] op_sel_hi:[1,0,1]
	v_pk_fma_f32 v[140:141], v[192:193], v[204:205], v[140:141] op_sel_hi:[1,0,1]
	v_pk_fma_f32 v[142:143], v[194:195], v[204:205], v[142:143] op_sel_hi:[1,0,1]
	v_pk_fma_f32 v[144:145], v[196:197], v[204:205], v[144:145] op_sel_hi:[1,0,1]
	v_pk_fma_f32 v[146:147], v[198:199], v[204:205], v[146:147] op_sel_hi:[1,0,1]
	v_pk_fma_f32 v[148:149], v[200:201], v[204:205], v[148:149] op_sel_hi:[1,0,1]
	v_pk_fma_f32 v[150:151], v[202:203], v[204:205], v[150:151] op_sel_hi:[1,0,1]
	v_pk_fma_f32 v[152:153], v[188:189], v[206:207], v[152:153] op_sel_hi:[1,0,1]
	v_pk_fma_f32 v[154:155], v[190:191], v[206:207], v[154:155] op_sel_hi:[1,0,1]
	v_pk_fma_f32 v[156:157], v[192:193], v[206:207], v[156:157] op_sel_hi:[1,0,1]
	v_pk_fma_f32 v[158:159], v[194:195], v[206:207], v[158:159] op_sel_hi:[1,0,1]
	v_pk_fma_f32 v[160:161], v[196:197], v[206:207], v[160:161] op_sel_hi:[1,0,1]
	v_pk_fma_f32 v[162:163], v[198:199], v[206:207], v[162:163] op_sel_hi:[1,0,1]
	v_pk_fma_f32 v[164:165], v[200:201], v[206:207], v[164:165] op_sel_hi:[1,0,1]
	v_pk_fma_f32 v[166:167], v[202:203], v[206:207], v[166:167] op_sel_hi:[1,0,1]
	s_waitcnt vmcnt(0)
	v_lshlrev_b32_e32 v188, 16, v128
	v_and_b32_e32 v189, 0xffff0000, v128
	v_lshlrev_b32_e32 v196, 16, v132
	v_and_b32_e32 v197, 0xffff0000, v132
	v_cmp_lt_u32_e32 vcc, 15, v209
	v_lshlrev_b32_e32 v190, 16, v129
	v_and_b32_e32 v191, 0xffff0000, v129
	v_lshlrev_b32_e32 v198, 16, v133
	v_and_b32_e32 v199, 0xffff0000, v133
	v_lshlrev_b32_e32 v192, 16, v130
	v_and_b32_e32 v193, 0xffff0000, v130
	v_lshlrev_b32_e32 v200, 16, v134
	v_and_b32_e32 v201, 0xffff0000, v134
	v_lshlrev_b32_e32 v194, 16, v131
	v_and_b32_e32 v195, 0xffff0000, v131
	v_lshlrev_b32_e32 v202, 16, v135
	v_and_b32_e32 v203, 0xffff0000, v135
	v_cndmask_b32_e32 v206, 0, v179, vcc
	v_pk_fma_f32 v[152:153], v[188:189], v[206:207], v[152:153] op_sel_hi:[1,0,1]
	v_pk_fma_f32 v[154:155], v[190:191], v[206:207], v[154:155] op_sel_hi:[1,0,1]
	v_pk_fma_f32 v[156:157], v[192:193], v[206:207], v[156:157] op_sel_hi:[1,0,1]
	v_pk_fma_f32 v[158:159], v[194:195], v[206:207], v[158:159] op_sel_hi:[1,0,1]
	v_pk_fma_f32 v[160:161], v[196:197], v[206:207], v[160:161] op_sel_hi:[1,0,1]
	v_pk_fma_f32 v[162:163], v[198:199], v[206:207], v[162:163] op_sel_hi:[1,0,1]
	v_pk_fma_f32 v[164:165], v[200:201], v[206:207], v[164:165] op_sel_hi:[1,0,1]
	v_pk_fma_f32 v[166:167], v[202:203], v[206:207], v[166:167] op_sel_hi:[1,0,1]
	v_cvt_f32_ubyte0_e32 v216, v208
	v_div_scale_f32 v217, s[2:3], v216, v216, 1.0
	v_rcp_f32_e32 v218, v217
	v_lshlrev_b32_e32 v188, 16, v0
	v_and_b32_e32 v189, 0xffff0000, v0
	v_lshlrev_b32_e32 v196, 16, v4
	v_and_b32_e32 v197, 0xffff0000, v4
	v_lshlrev_b32_e32 v190, 16, v1
	v_and_b32_e32 v191, 0xffff0000, v1
	v_lshlrev_b32_e32 v198, 16, v5
	v_and_b32_e32 v199, 0xffff0000, v5
	v_fma_f32 v219, -v217, v218, 1.0
	v_fmac_f32_e32 v218, v219, v218
	v_div_scale_f32 v220, vcc, 1.0, v216, 1.0
	v_mul_f32_e32 v221, v220, v218
	v_fma_f32 v222, -v217, v221, v220
	v_fmac_f32_e32 v221, v222, v218
	v_fma_f32 v217, -v217, v221, v220
	v_lshlrev_b32_e32 v192, 16, v2
	v_and_b32_e32 v193, 0xffff0000, v2
	v_div_fmas_f32 v217, v217, v218, v221
	v_div_fixup_f32 v216, v217, v216, 1.0
	v_lshlrev_b32_e32 v200, 16, v6
	v_and_b32_e32 v201, 0xffff0000, v6
	v_lshlrev_b32_e32 v194, 16, v3
	v_and_b32_e32 v195, 0xffff0000, v3
	v_lshlrev_b32_e32 v202, 16, v7
	v_and_b32_e32 v203, 0xffff0000, v7
	v_pk_fma_f32 v[136:137], v[216:217], v[136:137], v[188:189] op_sel_hi:[0,1,1] neg_lo:[0,0,1] neg_hi:[0,0,1]
	v_pk_fma_f32 v[138:139], v[216:217], v[138:139], v[190:191] op_sel_hi:[0,1,1] neg_lo:[0,0,1] neg_hi:[0,0,1]
	v_pk_fma_f32 v[140:141], v[216:217], v[140:141], v[192:193] op_sel_hi:[0,1,1] neg_lo:[0,0,1] neg_hi:[0,0,1]
	v_pk_fma_f32 v[142:143], v[216:217], v[142:143], v[194:195] op_sel_hi:[0,1,1] neg_lo:[0,0,1] neg_hi:[0,0,1]
	v_pk_fma_f32 v[144:145], v[216:217], v[144:145], v[196:197] op_sel_hi:[0,1,1] neg_lo:[0,0,1] neg_hi:[0,0,1]
	v_pk_fma_f32 v[146:147], v[216:217], v[146:147], v[198:199] op_sel_hi:[0,1,1] neg_lo:[0,0,1] neg_hi:[0,0,1]
	v_pk_fma_f32 v[148:149], v[216:217], v[148:149], v[200:201] op_sel_hi:[0,1,1] neg_lo:[0,0,1] neg_hi:[0,0,1]
	v_pk_fma_f32 v[150:151], v[216:217], v[150:151], v[202:203] op_sel_hi:[0,1,1] neg_lo:[0,0,1] neg_hi:[0,0,1]
	v_cvt_pk_bf16_f32 v136, v136, v137
	v_cvt_pk_bf16_f32 v137, v138, v139
	v_cvt_pk_bf16_f32 v138, v140, v141
	v_cvt_pk_bf16_f32 v139, v142, v143
	v_cvt_pk_bf16_f32 v140, v144, v145
	v_cvt_pk_bf16_f32 v141, v146, v147
	v_cvt_pk_bf16_f32 v142, v148, v149
	v_cvt_pk_bf16_f32 v143, v150, v151
	global_store_dwordx4 v211, v[136:139], s[50:51] offset:2048
	global_store_dwordx4 v211, v[140:143], s[50:51] offset:2064
	v_cvt_f32_ubyte0_e32 v216, v209
	v_div_scale_f32 v217, s[2:3], v216, v216, 1.0
	v_rcp_f32_e32 v218, v217
	v_lshlrev_b32_e32 v188, 16, v8
	v_and_b32_e32 v189, 0xffff0000, v8
	v_lshlrev_b32_e32 v196, 16, v12
	v_and_b32_e32 v197, 0xffff0000, v12
	v_lshlrev_b32_e32 v190, 16, v9
	v_and_b32_e32 v191, 0xffff0000, v9
	v_lshlrev_b32_e32 v198, 16, v13
	v_and_b32_e32 v199, 0xffff0000, v13
	v_fma_f32 v219, -v217, v218, 1.0
	v_fmac_f32_e32 v218, v219, v218
	v_div_scale_f32 v220, vcc, 1.0, v216, 1.0
	v_mul_f32_e32 v221, v220, v218
	v_fma_f32 v222, -v217, v221, v220
	v_fmac_f32_e32 v221, v222, v218
	v_fma_f32 v217, -v217, v221, v220
	v_lshlrev_b32_e32 v192, 16, v10
	v_and_b32_e32 v193, 0xffff0000, v10
	v_div_fmas_f32 v217, v217, v218, v221
	v_div_fixup_f32 v216, v217, v216, 1.0
	v_lshlrev_b32_e32 v200, 16, v14
	v_and_b32_e32 v201, 0xffff0000, v14
	v_lshlrev_b32_e32 v194, 16, v11
	v_and_b32_e32 v195, 0xffff0000, v11
	v_lshlrev_b32_e32 v202, 16, v15
	v_and_b32_e32 v203, 0xffff0000, v15
	v_pk_fma_f32 v[152:153], v[216:217], v[152:153], v[188:189] op_sel_hi:[0,1,1] neg_lo:[0,0,1] neg_hi:[0,0,1]
	v_pk_fma_f32 v[154:155], v[216:217], v[154:155], v[190:191] op_sel_hi:[0,1,1] neg_lo:[0,0,1] neg_hi:[0,0,1]
	v_pk_fma_f32 v[156:157], v[216:217], v[156:157], v[192:193] op_sel_hi:[0,1,1] neg_lo:[0,0,1] neg_hi:[0,0,1]
	v_pk_fma_f32 v[158:159], v[216:217], v[158:159], v[194:195] op_sel_hi:[0,1,1] neg_lo:[0,0,1] neg_hi:[0,0,1]
	v_pk_fma_f32 v[160:161], v[216:217], v[160:161], v[196:197] op_sel_hi:[0,1,1] neg_lo:[0,0,1] neg_hi:[0,0,1]
	v_pk_fma_f32 v[162:163], v[216:217], v[162:163], v[198:199] op_sel_hi:[0,1,1] neg_lo:[0,0,1] neg_hi:[0,0,1]
	v_pk_fma_f32 v[164:165], v[216:217], v[164:165], v[200:201] op_sel_hi:[0,1,1] neg_lo:[0,0,1] neg_hi:[0,0,1]
	v_pk_fma_f32 v[166:167], v[216:217], v[166:167], v[202:203] op_sel_hi:[0,1,1] neg_lo:[0,0,1] neg_hi:[0,0,1]
	v_cvt_pk_bf16_f32 v152, v152, v153
	v_cvt_pk_bf16_f32 v153, v154, v155
	v_cvt_pk_bf16_f32 v154, v156, v157
	v_cvt_pk_bf16_f32 v155, v158, v159
	v_cvt_pk_bf16_f32 v156, v160, v161
	v_cvt_pk_bf16_f32 v157, v162, v163
	v_cvt_pk_bf16_f32 v158, v164, v165
	v_cvt_pk_bf16_f32 v159, v166, v167
	global_store_dwordx4 v211, v[152:155], s[50:51] offset:0
	global_store_dwordx4 v211, v[156:159], s[50:51] offset:16
	s_add_i32 s1, s1, 1
	s_cmp_lt_u32 s1, 4
	s_cbranch_scc1 .Lpool_it
